# rwkv chain split moved 78 to 88 chunks (fewer chunks on the DUAL tiles that share CUs with ssd tiles); on top of compact rwkv scan loops, ssd prio 3 / rwkv prio 2, ssd tiles on blocks 384..431
# speedup vs baseline: 1.0357x; 1.0277x over previous
; __device__ __forceinline__ void phase_rwkvfix(const Params& p) {
;   for (int t = blockIdx.x; t < 32 * (NSEG1 / 64); t += gridDim.x) rwkv_fix_tile(p, t);
; __device__ __forceinline__ void phase_mixers(const Params& p, int l, unsigned char* smem) {
;     ...
;   const int bid = blockIdx.x, G = gridDim.x;
;   if (G == 512) {
;     if (bid < 128) {
;       __builtin_amdgcn_s_setprio(3);
;       rwkv_tile<false>(p, l, bid, smem);
;       __builtin_amdgcn_s_setprio(0);
;     } else if (bid < 256) {
;       __builtin_amdgcn_s_setprio(3);
;       rwkv_tile<true>(p, l, bid, smem);
;       __builtin_amdgcn_s_setprio(0);
;     } else if (bid < 304) {
;       __builtin_amdgcn_s_setprio(2);
;       ssd_tile(p, l, bid - 256, smem);
;       __builtin_amdgcn_s_setprio(0);
;     }
.LBB0_8:
	s_cmpk_gt_i32 s97, 0x3e8
	s_cselect_b64 s[2:3], -1, 0
	v_writelane_b32 v252, s2, 16
	s_add_u32 s0, s0, 0x198
	s_addc_u32 s1, s1, 0
	v_writelane_b32 v252, s3, 17
	v_writelane_b32 v252, s0, 18
	v_readlane_b32 s44, v251, 32
	v_readlane_b32 s52, v251, 40
	v_writelane_b32 v252, s1, 19
	s_add_u32 s0, s24, 0x200
	s_addc_u32 s1, s25, 0
	v_writelane_b32 v252, s0, 20
	v_readlane_b32 s53, v251, 41
	v_mov_b32_e32 v188, 0x100
	v_writelane_b32 v252, s1, 21
	s_add_u32 s0, s24, 0x1000
	s_addc_u32 s1, s25, 0
	v_writelane_b32 v252, s0, 22
	v_sub_co_u32_e32 v1, vcc, s93, v188
	s_nop 0
	v_writelane_b32 v252, s1, 23
	s_add_u32 s0, s24, 0x1100
	s_addc_u32 s1, s25, 0
	v_writelane_b32 v252, s0, 24
	s_movk_i32 s33, 0x300
	v_readlane_b32 s4, v251, 48
	v_writelane_b32 v252, s1, 25
	s_add_u32 s0, s24, 0x1200
	s_addc_u32 s1, s25, 0
	v_writelane_b32 v252, s0, 26
	v_readlane_b32 s18, v251, 62
	v_readlane_b32 s19, v251, 63
	v_writelane_b32 v252, s1, 27
	s_add_u32 s0, s24, 0x1300
	s_addc_u32 s1, s25, 0
	v_writelane_b32 v252, s0, 28
	s_cmp_eq_u32 s20, 15
	v_readlane_b32 s6, v251, 50
	v_writelane_b32 v252, s1, 29
	s_cselect_b64 s[0:1], -1, 0
	v_writelane_b32 v252, s0, 30
	s_cmp_eq_u32 s20, 14
	v_readlane_b32 s7, v251, 51
	v_writelane_b32 v252, s1, 31
	s_cselect_b64 s[0:1], -1, 0
	v_writelane_b32 v252, s0, 32
	s_cmp_eq_u32 s20, 13
	v_readlane_b32 s45, v251, 33
	v_writelane_b32 v252, s1, 33
	s_cselect_b64 s[0:1], -1, 0
	v_writelane_b32 v252, s0, 34
	s_cmp_eq_u32 s20, 12
	v_readlane_b32 s46, v251, 34
	v_writelane_b32 v252, s1, 35
	s_cselect_b64 s[0:1], -1, 0
	v_writelane_b32 v252, s0, 36
	s_cmp_eq_u32 s20, 11
	v_readlane_b32 s47, v251, 35
	v_writelane_b32 v252, s1, 37
	s_cselect_b64 s[0:1], -1, 0
	v_writelane_b32 v252, s0, 38
	s_cmp_eq_u32 s20, 10
	v_readlane_b32 s48, v251, 36
	v_writelane_b32 v252, s1, 39
	s_cselect_b64 s[0:1], -1, 0
	v_writelane_b32 v252, s0, 40
	s_cmp_eq_u32 s20, 9
	v_readlane_b32 s49, v251, 37
	v_writelane_b32 v252, s1, 41
	s_cselect_b64 s[0:1], -1, 0
	v_writelane_b32 v252, s0, 42
	s_cmp_eq_u32 s20, 8
	v_readlane_b32 s50, v251, 38
	v_writelane_b32 v252, s1, 43
	s_cselect_b64 s[0:1], -1, 0
	v_writelane_b32 v252, s0, 44
	s_cmp_eq_u32 s20, 7
	v_readlane_b32 s51, v251, 39
	v_writelane_b32 v252, s1, 45
	s_cselect_b64 s[0:1], -1, 0
	v_writelane_b32 v252, s0, 46
	s_cmp_eq_u32 s20, 6
	v_readlane_b32 s36, v251, 0
	v_writelane_b32 v252, s1, 47
	s_cselect_b64 s[0:1], -1, 0
	v_writelane_b32 v252, s0, 48
	s_cmp_eq_u32 s20, 5
	v_readlane_b32 s5, v251, 49
	v_writelane_b32 v252, s1, 49
	s_cselect_b64 s[0:1], -1, 0
	v_writelane_b32 v252, s0, 50
	s_cmp_eq_u32 s20, 4
	v_readlane_b32 s40, v251, 4
	v_writelane_b32 v252, s1, 51
	s_cselect_b64 s[0:1], -1, 0
	v_writelane_b32 v252, s0, 52
	s_cmp_eq_u32 s20, 3
	v_readlane_b32 s41, v251, 5
	v_writelane_b32 v252, s1, 53
	s_cselect_b64 s[0:1], -1, 0
	v_writelane_b32 v252, s0, 54
	s_cmp_eq_u32 s20, 2
	v_readlane_b32 s76, v251, 16
	v_writelane_b32 v252, s1, 55
	s_cselect_b64 s[0:1], -1, 0
	v_writelane_b32 v252, s0, 56
	s_cmp_eq_u32 s20, 1
	v_readlane_b32 s84, v251, 24
	v_writelane_b32 v252, s1, 57
	s_cselect_b64 s[0:1], -1, 0
	v_writelane_b32 v252, s0, 58
	s_cmp_eq_u32 s20, 0
	v_readlane_b32 s85, v251, 25
	v_writelane_b32 v252, s1, 59
	s_cselect_b64 s[0:1], -1, 0
	v_writelane_b32 v252, s0, 60
	v_readlane_b32 s86, v251, 26
	v_readlane_b32 s87, v251, 27
	v_writelane_b32 v252, s1, 61
	s_lshl_b32 s0, s20, 8
	s_add_u32 s0, s24, s0
	s_addc_u32 s1, s25, 0
	s_add_u32 s2, s0, 0x1400
	s_addc_u32 s3, s1, 0
	s_add_u32 s0, s0, 0x2400
	s_addc_u32 s1, s1, 0
	v_writelane_b32 v253, s0, 0
	v_writelane_b32 v252, s2, 62
	v_readfirstlane_b32 s20, v1
	s_sub_i32 s20, s93, 0x180
	v_writelane_b32 v253, s1, 1
	s_add_u32 s0, s24, 0x3400
	s_addc_u32 s1, s25, 0
	v_writelane_b32 v253, s0, 2
	v_writelane_b32 v252, s3, 63
	v_readlane_b32 s77, v251, 17
	v_writelane_b32 v253, s1, 3
	s_add_u32 s0, s24, 0x3500
	s_addc_u32 s1, s25, 0
	v_writelane_b32 v253, s0, 4
	s_cmpk_lt_i32 s93, 0x1000
	v_readlane_b32 s14, v251, 58
	v_writelane_b32 v253, s1, 5
	s_cselect_b64 s[0:1], -1, 0
	v_writelane_b32 v253, s0, 6
	s_cmp_eq_u32 s93, 0
	v_readlane_b32 s15, v251, 59
	v_writelane_b32 v253, s1, 7
	s_cselect_b64 s[0:1], -1, 0
	v_writelane_b32 v253, s0, 8
	s_cmpk_lt_i32 s93, 0x471
	v_readlane_b32 s37, v251, 1
	v_writelane_b32 v253, s1, 9
	s_cselect_b64 s[0:1], -1, 0
	v_writelane_b32 v253, s0, 10
	s_cmpk_lt_i32 s93, 0x1100
	v_readlane_b32 s8, v251, 52
	v_writelane_b32 v253, s1, 11
	s_cselect_b64 s[0:1], -1, 0
	v_writelane_b32 v253, s0, 12
	s_cmpk_lt_i32 s93, 0x300
	v_readlane_b32 s9, v251, 53
	v_writelane_b32 v253, s1, 13
	s_cselect_b64 s[0:1], -1, 0
	v_writelane_b32 v253, s0, 14
	s_cmpk_lt_i32 s93, 0x5a0
	v_readlane_b32 s10, v251, 54
	v_writelane_b32 v253, s1, 15
	s_cselect_b64 s[0:1], -1, 0
	v_writelane_b32 v253, s0, 16
	v_readlane_b32 s11, v251, 55
	v_readlane_b32 s54, v251, 42
	v_writelane_b32 v253, s1, 17
	s_add_u32 s0, s74, 0xe0c000
	s_addc_u32 s1, s75, 0
	v_writelane_b32 v253, s0, 18
	s_add_u32 s92, s52, 0x740000
	v_readlane_b32 s55, v251, 43
	v_writelane_b32 v253, s1, 19
	s_addc_u32 s0, s53, 0
	s_cmpk_lt_i32 s93, 0x2a8
	v_writelane_b32 v253, s0, 20
	s_cselect_b64 s[0:1], -1, 0
	v_writelane_b32 v253, s0, 21
	s_cmpk_gt_i32 s93, 0x7f
	s_mov_b32 s29, 0
	v_writelane_b32 v253, s1, 22
	s_cselect_b64 s[0:1], -1, 0
	v_writelane_b32 v253, s0, 23
	v_readlane_b32 s44, v251, 8
	v_readlane_b32 s45, v251, 9
	v_writelane_b32 v253, s1, 24
	s_xor_b64 s[0:1], vcc, -1
	v_writelane_b32 v253, s0, 25
	s_sub_i32 s0, s93, 0x180
	s_cmp_lt_u32 s0, 48
	v_readlane_b32 s48, v251, 12
	v_writelane_b32 v253, s1, 26
	s_cselect_b64 s[0:1], -1, 0
	v_writelane_b32 v253, s0, 27
	v_readlane_b32 s49, v251, 13
; template <bool DUAL>
; __device__ __forceinline__ void rwkv_tile(const Params& p, int l, int tile, unsigned char* smem) {
;   const int part = tile >> 7;
;   const int rg = tile & 3, h = (tile >> 2) & 3, b = (tile >> 4) & 3, d = (tile >> 6) & 1;
;   const int cbeg = (part == 0) ? 0 : CSPLIT, cend = (part == 0) ? CSPLIT : 136;
;   bf16_t* raw = (bf16_t*)smem;
;   bf16_t* pre = raw + 34 * 192;
;   float* rec = (float*)(smem + 13056 + 12288);
;   const int tid = launder(threadIdx.x), lane = tid & 63, w = tid >> 6, fr = lane & 15, fq = lane >> 4;
;   const int row = rg * 16 + w * 4 + fq;
;   const int c0 = fr * 4;
;   const int ld2 = l * 2 + d;
;   const size_t rowbase = (size_t)b * TPB;
;   const int lc = (tid & 15) * 4;
;   const float* mu0 = p.rwkv_mu + (size_t)(l * 2 + 0) * 1024 + h * 64 + lc;
;   const float* mu1 = p.rwkv_mu + (size_t)(l * 2 + 1) * 1024 + h * 64 + lc;
;   const float4 m0r = *(const float4*)mu0, m1r = *(const float4*)mu1;
;   const float4 m0k = *(const float4*)(mu0 + 256), m1k = *(const float4*)(mu1 + 256);
;   const float4 m0v = *(const float4*)(mu0 + 512), m1v = *(const float4*)(mu1 + 512);
;   const float4 ka4 = *(const float4*)(p.rwkv_k_a + ld2 * 256 + h * 64 + lc);
;   v2f sA = {0.f, 0.f}, sB = {0.f, 0.f};
; __device__ __forceinline__ void ssd_tile(const Params& p, int l, int tile, unsigned char* smem) {
;   const int h = tile % 6, b = (tile / 6) & 3, d = tile / 24, g = h / 3;
;   bf16_t* Cs0 = (bf16_t*)smem;
;   bf16_t* Bs = Cs0 + 2 * 32 * 136;
;   bf16_t* Xs = Bs + 32 * 136;
;   bf16_t* BtT = Xs + 32 * 72;
;   bf16_t* XdT = BtT + 128 * 40;
;   bf16_t* Ms = XdT + 64 * 40;
;   bf16_t* Sb = Ms + 32 * 40;
;   float* dc = (float*)(Sb + 64 * 136);
;   const int tid = launder(threadIdx.x), lane = tid & 63, w = tid >> 6, fr = lane & 15, fq = lane >> 4;
;   const size_t rowbase = (size_t)b * TPB;
;   f32x4 S[4][2];
; #pragma unroll
;   for (int i = 0; i < 4; ++i)
; #pragma unroll
;     for (int j = 0; j < 2; ++j) S[i][j] = (f32x4){0.f, 0.f, 0.f, 0.f};
;   const int pcc = tid % 40, prow = tid / 40;
;   const bool pact = tid < 240;
;   const int pcol = (pcc < 16) ? (640 + g * 128 + pcc * 8) : ((pcc < 32) ? (384 + g * 128 + (pcc - 16) * 8) : (h * 64 + (pcc - 32) * 8));
;   const bf16_t* pbase = p.PS + rowbase * 912 + pcol;
;   const float2* dbase = p.DTC + (size_t)(d * 6 + h) * TOK + rowbase;
	v_readlane_b32 s56, v251, 44
	v_writelane_b32 v253, s1, 28
	s_sub_i32 s0, s93, 0x180
	s_mov_b32 s3, s0
	s_mulk_i32 s0, 0xab
	s_lshr_b32 s1, s0, 10
	s_mul_i32 s1, s1, 6
	s_sub_i32 s1, s3, s1
	s_and_b32 s3, s1, 0xff
	s_bfe_u32 s2, s0, 0x2000a
	s_lshl_b32 s0, s3, 6
	s_addk_i32 s0, 0xff00
	v_writelane_b32 v253, s0, 29
	s_cmp_gt_u32 s3, 2
	s_movk_i32 s0, 0x180
	s_cselect_b32 s0, s0, 0x100
	v_writelane_b32 v253, s0, 30
	s_cselect_b32 s0, s33, 0x280
	v_writelane_b32 v253, s0, 31
	s_mul_i32 s0, s2, 0x792000
	s_add_u32 s0, s18, s0
	s_addc_u32 s1, s19, 0
	v_writelane_b32 v253, s0, 32
	s_cmp_lt_u32 s20, 24
	v_readlane_b32 s57, v251, 45
	v_writelane_b32 v253, s1, 33
	s_cselect_b64 s[0:1], -1, 0
	v_writelane_b32 v253, s0, 34
	v_readlane_b32 s58, v251, 46
	v_readlane_b32 s59, v251, 47
	v_writelane_b32 v253, s1, 35
	v_writelane_b32 v253, s60, 36
	s_and_b64 s[0:1], s[0:1], exec
	s_movk_i32 s0, 0x10e0
	v_writelane_b32 v253, s61, 37
	v_writelane_b32 v253, s62, 38
	v_writelane_b32 v253, s63, 39
	v_writelane_b32 v253, s64, 40
	v_writelane_b32 v253, s65, 41
	v_writelane_b32 v253, s66, 42
	v_writelane_b32 v253, s67, 43
	v_writelane_b32 v253, s68, 44
	v_writelane_b32 v253, s69, 45
	v_writelane_b32 v253, s70, 46
	v_writelane_b32 v253, s71, 47
	v_writelane_b32 v253, s72, 48
	s_cselect_b32 s4, 0, 0xe0
	s_cselect_b32 s0, s0, 0x100
	s_cmp_gt_u32 s20, 23
	v_writelane_b32 v253, s73, 49
	s_mul_i32 s1, s2, 0x1100
	s_cselect_b32 s2, 6, 0
	v_writelane_b32 v253, s74, 50
	s_cselect_b32 s20, 0x4400, 0
	s_add_i32 s2, s2, s3
	v_writelane_b32 v253, s75, 51
	v_readlane_b32 s60, v252, 0
	s_mul_i32 s2, s2, 0x22000
	v_readlane_b32 s68, v252, 8
	v_readlane_b32 s69, v252, 9
	s_add_u32 s2, s68, s2
	s_addc_u32 s21, s69, 0
	s_lshl_b32 s22, s1, 3
	s_add_u32 s6, s2, s22
	s_addc_u32 s7, s21, 0
	v_writelane_b32 v253, s6, 52
	s_or_b32 s2, s4, 6
	v_readlane_b32 s62, v252, 2
	v_writelane_b32 v253, s7, 53
	v_writelane_b32 v253, s2, 54
	s_or_b32 s2, s4, 12
	v_writelane_b32 v253, s2, 55
	s_or_b32 s2, s4, 18
	v_writelane_b32 v253, s2, 56
	s_or_b32 s2, s4, 24
	v_writelane_b32 v253, s2, 57
	s_add_i32 s6, s1, s20
	s_lshl_b32 s1, s3, 7
	v_writelane_b32 v253, s4, 58
	s_or_b32 s2, s4, 30
	v_readlane_b32 s63, v252, 3
	v_writelane_b32 v253, s2, 59
	s_add_u32 s2, s62, s1
	s_addc_u32 s3, s63, 0
	v_writelane_b32 v253, s2, 60
	s_bfe_u32 s1, s93, 0x20004
	s_lshr_b32 s21, s93, 6
	v_writelane_b32 v253, s3, 61
	s_lshl_b32 s2, s93, 4
	s_and_b32 s3, s2, 48
	v_writelane_b32 v253, s3, 62
	v_writelane_b32 v253, s2, 63
	s_and_b32 s2, s2, 0xc0
	s_bfe_u32 s4, s93, 0x10006
	s_lshl_b32 s3, s2, 2
	s_add_u32 s5, s40, s3
	v_writelane_b32 v254, s5, 0
	s_addc_u32 s5, s41, 0
	v_writelane_b32 v254, s5, 1
	v_writelane_b32 v254, s24, 2
	s_add_u32 s3, s76, s3
	s_mul_i32 s20, s1, 0x1100
	v_writelane_b32 v254, s25, 3
	v_writelane_b32 v254, s26, 4
	v_writelane_b32 v254, s27, 5
	v_readlane_b32 s64, v252, 4
	v_readlane_b32 s84, v254, 2
	v_readlane_b32 s85, v254, 3
	v_readlane_b32 s86, v254, 4
	v_readlane_b32 s87, v254, 5
	v_writelane_b32 v254, s3, 6
	s_addc_u32 s3, s77, 0
	v_writelane_b32 v254, s3, 7
	s_lshl_b32 s3, s20, 11
	s_add_u32 s22, s14, s3
	s_addc_u32 s23, s15, 0
	s_lshl_b32 s24, s2, 1
	s_add_u32 s2, s22, s24
	s_addc_u32 s3, s23, 0
	v_writelane_b32 v254, s2, 8
	v_readlane_b32 s65, v252, 5
	s_movk_i32 s5, 0x10ff
	v_writelane_b32 v254, s3, 9
	s_lshl_b32 s2, s20, 10
	s_add_u32 s2, s64, s2
	s_addc_u32 s3, s65, 0
	s_lshl_b32 s25, s4, 9
	s_add_u32 s25, s2, s25
	s_addc_u32 s26, s3, 0
	s_add_u32 s2, s25, s24
	s_addc_u32 s3, s26, 0
	v_writelane_b32 v254, s2, 10
	s_cmpk_lt_u32 s93, 0x80
	v_readlane_b32 s61, v252, 1
	v_writelane_b32 v254, s3, 11
	s_cselect_b64 s[2:3], -1, 0
	v_writelane_b32 v254, s2, 12
	v_readlane_b32 s70, v252, 10
	v_readlane_b32 s71, v252, 11
	v_writelane_b32 v254, s3, 13
	s_and_b64 s[2:3], s[2:3], exec
	s_movk_i32 s2, 0x88
	s_cselect_b32 s2, 0x58, s2
	s_cselect_b32 s3, 0, 0x58
	v_writelane_b32 v254, s2, 14
	s_movk_i32 s2, 0x11e0
	s_cselect_b32 s5, 0xff, s5
	s_cselect_b32 s2, 0xe0, s2
	v_writelane_b32 v254, s5, 15
	s_cselect_b32 s5, 0, 0x100
	s_lshl_b32 s27, s3, 5
	s_sub_i32 s28, s2, s27
	s_cmp_eq_u32 s4, 0
	v_writelane_b32 v254, s5, 16
	s_cselect_b64 s[36:37], -1, 0
	v_writelane_b32 v254, s3, 17
	s_and_b64 s[2:3], s[36:37], exec
	s_movk_i32 s2, 0xb00
	s_cselect_b32 s3, s2, 0x6e0
	s_mul_i32 s2, s4, 0x4400
	s_cselect_b32 s5, s27, s28
	s_add_i32 s20, s2, s20
	v_writelane_b32 v254, s4, 18
	s_lshl_b32 s2, s4, 2
	s_or_b32 s2, s2, s1
	v_writelane_b32 v254, s3, 19
	s_add_i32 s3, s3, -1
	s_add_u32 s8, s60, s24
	v_writelane_b32 v254, s3, 20
	s_addc_u32 s9, s61, 0
	v_writelane_b32 v254, s8, 21
	s_mulk_i32 s2, 0x600
	s_mov_b32 s7, s29
	v_writelane_b32 v254, s9, 22
	s_add_u32 s8, s70, s24
	s_addc_u32 s9, s71, 0
	s_bfe_u32 s3, s93, 0x20002
	v_writelane_b32 v254, s8, 23
	s_lshl_b32 s24, s3, 8
	s_add_u32 s4, s40, s24
	v_writelane_b32 v254, s9, 24
	v_writelane_b32 v254, s4, 25
	s_addc_u32 s4, s41, 0
	v_writelane_b32 v254, s4, 26
	s_add_u32 s4, s76, s24
	v_writelane_b32 v254, s4, 27
	s_addc_u32 s4, s77, 0
	s_lshl_b32 s24, s3, 7
	s_add_u32 s8, s22, s24
	v_writelane_b32 v254, s4, 28
	s_addc_u32 s9, s23, 0
	v_writelane_b32 v254, s8, 29
	v_and_b32_e32 v189, 0x3ff, v0
	v_and_b32_e32 v0, 0x3fffffff, v0
	v_writelane_b32 v254, s9, 30
	s_add_u32 s8, s25, s24
	s_addc_u32 s9, s26, 0
	v_writelane_b32 v254, s8, 31
	s_add_i32 s4, s5, -1
	v_mbcnt_lo_u32_b32 v1, -1, 0
	v_writelane_b32 v254, s9, 32
	v_writelane_b32 v254, s5, 33
	v_writelane_b32 v254, s4, 34
	s_add_u32 s4, s60, s24
	s_addc_u32 s5, s61, 0
	s_lshl_b32 s21, s21, 4
	s_lshl_b32 s1, s1, 2
	s_or_b32 s1, s1, s21
	v_writelane_b32 v254, s4, 35
	s_or_b32 s1, s1, s3
	s_lshl_b32 s1, s1, 6
; #define LAS __attribute__((address_space(3)))
; __device__ void sincos_d(double x, float& c, float& s) {
;   double n = rint(x * 0.63661977236758134308);
;   double r = x - n * 1.57079632679489661923;
;   double r2 = r * r;
;   double sn = r * (1.0 + r2 * (-1.0 / 6 + r2 * (1.0 / 120 + r2 * (-1.0 / 5040 + r2 * (1.0 / 362880 + r2 * (-1.0 / 39916800 + r2 * (1.0 / 6227020800.0)))))));
;   double cs = 1.0 + r2 * (-0.5 + r2 * (1.0 / 24 + r2 * (-1.0 / 720 + r2 * (1.0 / 40320 + r2 * (-1.0 / 3628800 + r2 * (1.0 / 479001600.0 + r2 * (-1.0 / 87178291200.0)))))));
; __global__ void __launch_bounds__(NTHREADS, LBW) mega(Params p, int ph_lo, int ph_hi) {
;   extern __shared__ __attribute__((aligned(16))) unsigned char smem[];
;   volatile LAS unsigned* xst = (volatile LAS unsigned*)(smem + LDS_BYTES - 16);
;   XcdBarrier xb;
;   xb.bar = p.bar; xb.x = 0; xb.st = xst;
;   if (ph_hi - ph_lo > 1) {
;     if (threadIdx.x == 0) { xst[0] = 0u; xst[1] = 0u; }
;     __syncthreads();
;     xb = xcd_barrier_post(p.bar, xst);
;   }
	v_writelane_b32 v254, s5, 36
	v_writelane_b32 v254, s2, 37
	s_cmpk_lt_i32 s93, 0x860
	v_writelane_b32 v254, s1, 38
	s_cselect_b64 s[2:3], -1, 0
	v_writelane_b32 v254, s2, 39
	s_cmpk_lt_i32 s93, 0xcc0
	v_readlane_b32 s66, v252, 6
	v_writelane_b32 v254, s3, 40
	s_cselect_b64 s[2:3], -1, 0
	v_writelane_b32 v254, s2, 41
	s_cmpk_lt_i32 s93, 0x600
	v_readlane_b32 s67, v252, 7
	v_writelane_b32 v254, s3, 42
	s_cselect_b64 s[2:3], -1, 0
	v_writelane_b32 v254, s2, 43
	s_cmpk_lt_i32 s93, 0xc0
	v_readlane_b32 s72, v252, 12
	v_writelane_b32 v254, s3, 44
	s_cselect_b64 s[2:3], -1, 0
	v_writelane_b32 v254, s2, 45
	s_cmpk_lt_i32 s93, 0x440
	v_readlane_b32 s73, v252, 13
	v_writelane_b32 v254, s3, 46
	s_cselect_b64 s[2:3], -1, 0
	s_and_b32 s1, s93, 7
	v_writelane_b32 v254, s2, 47
	s_cmpk_lt_u32 s93, 0x440
	v_readlane_b32 s74, v252, 14
	v_writelane_b32 v254, s3, 48
	s_cselect_b64 s[2:3], -1, 0
	v_writelane_b32 v254, s2, 49
	v_readlane_b32 s75, v252, 15
	v_mbcnt_hi_u32_b32 v192, -1, v1
	v_writelane_b32 v254, s3, 50
	s_lshr_b32 s2, s93, 3
	s_lshl_b32 s3, s93, 2
	s_add_u32 s4, s10, 0x80
	v_writelane_b32 v254, s3, 51
	s_addc_u32 s5, s11, 0
	v_writelane_b32 v254, s4, 52
	s_add_u32 s3, s52, 0x80
	v_readlane_b32 s16, v251, 60
	v_writelane_b32 v254, s5, 53
	v_writelane_b32 v254, s3, 54
	s_addc_u32 s3, s53, 0
	s_add_u32 s4, s10, 64
	v_writelane_b32 v254, s3, 55
	s_addc_u32 s5, s11, 0
	v_writelane_b32 v254, s4, 56
	s_add_u32 s3, s52, 64
	v_readlane_b32 s17, v251, 61
	v_writelane_b32 v254, s5, 57
	v_writelane_b32 v254, s3, 58
	s_addc_u32 s3, s53, 0
	v_writelane_b32 v254, s3, 59
	s_add_u32 s3, s54, 0x80
	v_writelane_b32 v254, s3, 60
	s_addc_u32 s3, s55, 0
	v_writelane_b32 v254, s3, 61
	v_writelane_b32 v254, s6, 62
	s_add_i32 s0, s6, s0
	v_writelane_b32 v255, s0, 0
	s_mov_b32 s0, s44
	v_writelane_b32 v255, s0, 1
	s_mov_b32 s0, s45
	v_writelane_b32 v255, s0, 2
	s_mov_b32 s0, s44
	v_writelane_b32 v255, s0, 3
	s_mov_b32 s0, s45
	v_writelane_b32 v255, s0, 4
	s_mov_b32 s0, s48
	v_writelane_b32 v255, s0, 5
	s_mov_b32 s0, s49
	v_writelane_b32 v255, s0, 6
	s_mov_b32 s0, s48
	v_writelane_b32 v255, s0, 7
	s_mov_b32 s0, s49
	v_writelane_b32 v255, s0, 8
	s_mov_b32 s0, s56
	v_writelane_b32 v255, s0, 9
	s_mov_b32 s0, s57
	v_writelane_b32 v255, s0, 10
	s_mov_b32 s0, s56
	v_writelane_b32 v255, s0, 11
	s_mov_b32 s0, s57
	v_writelane_b32 v255, s0, 12
	s_mov_b32 s0, s58
	v_writelane_b32 v255, s0, 13
	s_mov_b32 s0, s59
	v_writelane_b32 v255, s0, 14
	s_mov_b32 s0, s58
	v_writelane_b32 v255, s0, 15
	s_mov_b32 s0, s59
	v_writelane_b32 v255, s0, 16
	s_lshl_b32 s0, s93, 7
	v_writelane_b32 v255, s0, 17
	v_writelane_b32 v255, s1, 18
	s_lshl_b32 s0, s1, 7
	v_writelane_b32 v255, s0, 19
	v_writelane_b32 v255, s2, 20
	s_lshl_b32 s0, s2, 7
	v_writelane_b32 v255, s0, 21
	s_add_i32 s0, 0, 0x12bf0
	v_writelane_b32 v255, s0, 22
	s_add_i32 s0, 0, 0x12bf4
	v_writelane_b32 v255, s0, 23
	s_add_i32 s0, 0, 0x103fc
	v_writelane_b32 v255, s0, 24
	s_add_i32 s0, 0, 0x10380
	v_writelane_b32 v255, s0, 25
	s_add_i32 s0, 0, 0x6e00
	v_writelane_b32 v255, s0, 26
	s_add_i32 s0, 0, 0x6900
	v_writelane_b32 v255, s0, 27
	s_add_i32 s0, 0, 0x12000
	v_writelane_b32 v255, s0, 28
	s_add_i32 s0, 0, 0x700
	v_writelane_b32 v255, s0, 29
	s_add_i32 s0, 0, 0x6600
	v_writelane_b32 v255, s0, 30
	v_cmp_eq_u32_e64 s[2:3], 0, v0
	s_mov_b32 s0, s96
	v_readlane_b32 s38, v251, 2
	v_writelane_b32 v255, s2, 31
	v_readlane_b32 s39, v251, 3
	v_readlane_b32 s88, v251, 28
	v_writelane_b32 v255, s3, 32
	v_cmp_eq_u32_e64 s[2:3], 0, v189
	v_readlane_b32 s89, v251, 29
	v_readlane_b32 s90, v251, 30
	v_writelane_b32 v255, s2, 33
	v_readlane_b32 s91, v251, 31
	v_readlane_b32 s60, v253, 36
	v_writelane_b32 v255, s3, 34
	v_writelane_b32 v255, s96, 35
	v_and_b32_e32 v1, 64, v192
	v_readlane_b32 s62, v253, 38
	v_writelane_b32 v255, s97, 36
	v_writelane_b32 v255, s92, 37
	v_readlane_b32 s63, v253, 39
	s_mov_b32 s21, s29
	v_mov_b32_e32 v164, 0
	v_mov_b32_e32 v190, 1
	v_mov_b32_e32 v191, 0x358637bd
	v_add_u32_e32 v193, 64, v1
	v_xor_b32_e32 v194, 32, v192
	v_xor_b32_e32 v195, 16, v192
	v_xor_b32_e32 v196, 8, v192
	v_xor_b32_e32 v197, 4, v192
	v_xor_b32_e32 v198, 2, v192
	v_xor_b32_e32 v199, 1, v192
	v_mov_b32_e32 v200, 0x10ff
	v_mov_b32_e32 v201, 0xff
	v_mov_b32_e32 v166, 0x3727c5ac
	v_mov_b32_e32 v167, 0x3a27c5ac
	v_mov_b32_e32 v202, 0x600
	v_mov_b32_e32 v203, 0x11ff
	v_mov_b32_e32 v204, 0x80
	v_mov_b32_e32 v205, 0xff800000
	v_writelane_b32 v254, s7, 63
	v_mov_b32_e32 v206, 0x41b17218
	v_mov_b32_e32 v207, 0x7f
	v_mov_b32_e32 v208, 0xf500
	v_mov_b32_e32 v209, 0x420
	v_mov_b32_e32 v210, 0x1ef0
	v_mov_b32_e32 v211, 0x2100
	v_mov_b32_e32 v212, 0x2310
	v_mov_b32_e32 v213, 0x2520
	v_mov_b32_e32 v214, 0x42800000
	v_not_b32_e32 v215, 63
	v_mov_b32_e32 v168, 0x67f544e4
	v_mov_b32_e32 v169, 0xbe5ae645
	v_mov_b32_e32 v170, 0xa556c734
	v_mov_b32_e32 v171, 0x3ec71de3
	v_mov_b32_e32 v172, 0x1a01a01a
	v_mov_b32_e32 v173, 0xbf2a01a0
	v_mov_b32_e32 v174, 0x11111111
	v_mov_b32_e32 v175, 0x3f811111
	v_mov_b32_e32 v176, 0x55555555
	v_mov_b32_e32 v177, 0xbfc55555
	v_mov_b32_e32 v178, 0xeff8d898
	v_mov_b32_e32 v179, 0x3e21eed8
	v_mov_b32_e32 v180, 0xb7789f5c
	v_mov_b32_e32 v181, 0xbe927e4f
	v_mov_b32_e32 v183, 0x3efa01a0
	v_mov_b32_e32 v184, 0x16c16c17
	v_mov_b32_e32 v185, 0xbf56c16c
	v_mov_b32_e32 v187, 0x3fa55555
	s_movk_i32 s31, 0x1000
	s_movk_i32 s40, 0xff
	s_mov_b32 s27, 0x10000
	s_mov_b32 s38, 0x78787879
	s_movk_i32 s39, 0x720
	s_movk_i32 s34, 0x104
	s_movk_i32 s35, 0x3830
	s_movk_i32 s41, 0x3000
	s_mov_b32 s26, 0x20000
	s_mov_b32 s90, 0x30000
	s_mov_b32 s91, 0x40000
	s_mov_b32 s88, 0x60000
	s_movk_i32 s89, 0xfefe
	s_mov_b64 s[22:23], 0x1100
	s_mov_b64 s[16:17], 0x20100
	s_mov_b64 s[24:25], 0x40100
	s_mov_b64 s[18:19], 0x60100
	s_mov_b32 s30, 0x3e000000
	v_writelane_b32 v255, s93, 38
	v_readlane_b32 s12, v251, 56
	v_readlane_b32 s13, v251, 57
	v_readlane_b32 s42, v251, 6
	v_readlane_b32 s43, v251, 7
	v_readlane_b32 s46, v251, 10
	v_readlane_b32 s47, v251, 11
	v_readlane_b32 s50, v251, 14
	v_readlane_b32 s51, v251, 15
	v_readlane_b32 s78, v251, 18
	v_readlane_b32 s79, v251, 19
	v_readlane_b32 s80, v251, 20
	v_readlane_b32 s81, v251, 21
	v_readlane_b32 s82, v251, 22
	v_readlane_b32 s83, v251, 23
	v_readlane_b32 s61, v253, 37
	v_readlane_b32 s64, v253, 40
	v_readlane_b32 s65, v253, 41
	v_readlane_b32 s66, v253, 42
	v_readlane_b32 s67, v253, 43
	v_readlane_b32 s68, v253, 44
	v_readlane_b32 s69, v253, 45
	v_readlane_b32 s70, v253, 46
	v_readlane_b32 s71, v253, 47
	v_readlane_b32 s72, v253, 48
	v_readlane_b32 s73, v253, 49
	v_readlane_b32 s74, v253, 50
	v_readlane_b32 s75, v253, 51
	s_branch .LBB0_11

; __device__ __forceinline__ float bf2f(bf16_t v) { return __uint_as_float(((unsigned)v) << 16); }
; __device__ __forceinline__ bf16_t f2bf(float f) { return (bf16_t)(pack2(f, 0.f) & 0xffffu); }
; __device__ __forceinline__ int launder(int x) { asm volatile("" : "+v"(x)); return x; }
; #define MFMA(a, b, c) __builtin_amdgcn_mfma_f32_16x16x32_bf16(a, b, c, 0, 0, 0)
; __device__ __forceinline__ void rwkv_fix_tile(const Params& p, int tile) {
;   const int mb = tile % (NSEG1 / 64), dbh = tile / (NSEG1 / 64), h = dbh & 3, b = (dbh >> 2) & 3, d = dbh >> 4;
;   const int tid = launder(threadIdx.x), lane = tid & 63, w = tid >> 6, fr = lane & 15, fq = lane >> 4;
;   const size_t rowbase = (size_t)b * TPB;
;   const int s0 = mb * 64 + 16 * w;
;   const bf16_t* gp = p.GID + ((size_t)(d * 4 + b) * NSEG1 + s0 + fr) * 256 + h * 64 + fq * 8;
;   const bf16x8 a0 = *(const bf16x8*)gp, a1 = *(const bf16x8*)(gp + 32);
; #pragma unroll
;   for (int nt = 0; nt < 4; ++nt) {
;     const float* sp = p.SMID + ((size_t)(dbh * 64 + nt * 16 + fr)) * 64 + fq * 8;
;     const float4 f0 = *(const float4*)sp, f1 = *(const float4*)(sp + 4), f2 = *(const float4*)(sp + 32), f3 = *(const float4*)(sp + 36);
;     union { unsigned u[4]; bf16x8 v; } b0, b1;
;     b0.u[0] = pack2(f0.x, f0.y); b0.u[1] = pack2(f0.z, f0.w); b0.u[2] = pack2(f1.x, f1.y); b0.u[3] = pack2(f1.z, f1.w);
;     b1.u[0] = pack2(f2.x, f2.y); b1.u[1] = pack2(f2.z, f2.w); b1.u[2] = pack2(f3.x, f3.y); b1.u[3] = pack2(f3.z, f3.w);
;     f32x4 acc = (f32x4){0.f, 0.f, 0.f, 0.f};
;     acc = MFMA(a0, b0.v, acc);
;     acc = MFMA(a1, b1.v, acc);
; #pragma unroll
;     for (int j = 0; j < 4; ++j) {
;       const int st = CSPLIT * 32 + s0 + fq * 4 + j;
;       const int pp = (d == 0) ? st : ((st < 256) ? 255 - st : 4607 - st);
;       bf16_t* yp = p.yR + ((size_t)d * TOK + rowbase + pp) * 256 + h * 64 + nt * 16 + fr;
;       *yp = f2bf(bf2f(*yp) + acc[j]);
;     }
;   }
; }
.LBB0_123:
	s_mul_i32 s28, s46, 0xaaab
	v_mov_b32_e32 v0, v189
	s_lshr_b32 s44, s28, 20
	s_mul_i32 s28, s44, 24
	v_and_b32_e32 v12, 15, v0
	v_bfe_u32 v13, v0, 4, 2
	v_ashrrev_i32_e32 v0, 2, v0
	s_sub_i32 s28, s46, s28
	s_ashr_i32 s45, s44, 4
	v_and_b32_e32 v0, -16, v0
	s_bfe_u32 s42, s44, 0x20002
	v_lshl_add_u32 v8, s28, 6, v0
	s_lshl_b32 s28, s45, 2
	s_or_b32 s28, s28, s42
	v_ashrrev_i32_e32 v9, 31, v8
	s_mul_i32 s47, s42, 0x1100
	v_mad_i64_i32 v[0:1], s[42:43], s28, v202, v[8:9]
	v_or_b32_e32 v0, v0, v12
	v_lshlrev_b64 v[0:1], 9, v[0:1]
	s_lshl_b32 s28, s44, 7
	v_lshl_or_b32 v16, s44, 6, v12
	v_lshl_add_u64 v[0:1], s[10:11], 0, v[0:1]
	s_and_b32 s28, s28, 0x180
	v_lshlrev_b32_e32 v10, 5, v13
	v_mov_b32_e32 v11, v164
	v_ashrrev_i32_e32 v17, 31, v16
	v_lshl_add_u64 v[0:1], v[0:1], 0, s[28:29]
	v_lshlrev_b32_e32 v2, 4, v13
	v_mov_b32_e32 v3, v164
	v_lshl_add_u64 v[18:19], s[12:13], 0, v[10:11]
	v_lshlrev_b64 v[10:11], 8, v[16:17]
	v_lshl_add_u64 v[4:5], v[0:1], 0, v[2:3]
	s_waitcnt vmcnt(0)
	v_lshl_add_u64 v[28:29], v[18:19], 0, v[10:11]
	global_load_dwordx4 v[0:3], v[4:5], off
	s_nop 0
	global_load_dwordx4 v[4:7], v[4:5], off offset:64
	v_lshl_or_b32 v32, v13, 2, v8
	v_lshlrev_b32_e32 v8, 1, v12
	global_load_dwordx4 v[10:13], v[28:29], off offset:16
	global_load_dwordx4 v[20:23], v[28:29], off
	global_load_dwordx4 v[24:27], v[28:29], off offset:144
	s_nop 0
	global_load_dwordx4 v[28:31], v[28:29], off offset:128
	s_cmp_lt_u32 s44, 16
	s_mul_hi_i32 s42, s45, 0x4400
	s_mulk_i32 s45, 0x4400
	s_cselect_b64 vcc, -1, 0
	s_add_u32 s44, s45, s47
	s_addc_u32 s45, s42, 0
	s_add_u32 s42, s0, s28
	v_add_u32_e32 v33, 0xb00, v32
	s_addc_u32 s43, s1, 0
	v_mov_b32_e32 v9, v164
	v_lshl_add_u64 v[14:15], s[42:43], 0, v[8:9]
	v_cmp_lt_i32_e64 s[42:43], s40, v33
	s_waitcnt vmcnt(2)
	v_cvt_pk_bf16_f32 v20, v20, v21
	v_cndmask_b32_e64 v8, v201, v203, s[42:43]
	v_sub_u32_e32 v8, v8, v33
	v_cndmask_b32_e32 v8, v8, v33, vcc
	v_cvt_pk_bf16_f32 v21, v22, v23
	v_cvt_pk_bf16_f32 v22, v10, v11
	v_cvt_pk_bf16_f32 v23, v12, v13
	v_ashrrev_i32_e32 v9, 31, v8
	v_lshl_add_u64 v[8:9], s[44:45], 0, v[8:9]
	v_mfma_f32_16x16x32_bf16 v[20:23], v[0:3], v[20:23], 0
	v_lshlrev_b64 v[8:9], 9, v[8:9]
	s_waitcnt vmcnt(0)
	v_cvt_pk_bf16_f32 v10, v28, v29
	v_cvt_pk_bf16_f32 v11, v30, v31
	v_cvt_pk_bf16_f32 v12, v24, v25
	v_cvt_pk_bf16_f32 v13, v26, v27
	v_lshl_add_u64 v[8:9], v[14:15], 0, v[8:9]
	v_cmp_gt_i32_e64 s[42:43], s40, v33
	v_mfma_f32_16x16x32_bf16 v[20:23], v[4:7], v[10:13], v[20:23]
	global_load_ushort v10, v[8:9], off
	v_cndmask_b32_e64 v11, v203, v201, s[42:43]
	s_waitcnt vmcnt(0)
	v_lshlrev_b32_e32 v10, 16, v10
	s_nop 3
	v_add_f32_e32 v10, v20, v10
	v_cvt_pk_bf16_f32 v10, v10, s0
	global_store_short v[8:9], v10, off
	v_add_u32_e32 v10, 0xb01, v32
	v_sub_u32_e32 v11, v11, v10
	v_cndmask_b32_e32 v10, v11, v10, vcc
	v_ashrrev_i32_e32 v11, 31, v10
	v_lshl_add_u64 v[10:11], s[44:45], 0, v[10:11]
	v_lshlrev_b64 v[10:11], 9, v[10:11]
	v_lshl_add_u64 v[10:11], v[14:15], 0, v[10:11]
	global_load_ushort v12, v[10:11], off
	s_waitcnt vmcnt(0)
	v_lshlrev_b32_e32 v12, 16, v12
	v_add_f32_e32 v12, v21, v12
	v_cvt_pk_bf16_f32 v12, v12, s0
	global_store_short v[10:11], v12, off
	v_add_u32_e32 v12, 0xb02, v32
	v_cmp_lt_i32_e64 s[42:43], s40, v12
	s_nop 1
	v_cndmask_b32_e64 v13, v201, v203, s[42:43]
	v_sub_u32_e32 v13, v13, v12
	v_cndmask_b32_e32 v12, v13, v12, vcc
	v_ashrrev_i32_e32 v13, 31, v12
	v_lshl_add_u64 v[12:13], s[44:45], 0, v[12:13]
	v_lshlrev_b64 v[12:13], 9, v[12:13]
	v_lshl_add_u64 v[12:13], v[14:15], 0, v[12:13]
	global_load_ushort v17, v[12:13], off
	s_waitcnt vmcnt(0)
	v_lshlrev_b32_e32 v17, 16, v17
	v_add_f32_e32 v17, v22, v17
	v_cvt_pk_bf16_f32 v17, v17, s0
	global_store_short v[12:13], v17, off
	v_add_u32_e32 v17, 0xb03, v32
	v_cmp_lt_i32_e64 s[42:43], s40, v17
	s_nop 1
	v_cndmask_b32_e64 v20, v201, v203, s[42:43]
	v_sub_u32_e32 v20, v20, v17
	v_cndmask_b32_e32 v20, v20, v17, vcc
	v_ashrrev_i32_e32 v21, 31, v20
	v_lshl_add_u64 v[20:21], s[44:45], 0, v[20:21]
	v_lshlrev_b64 v[20:21], 9, v[20:21]
	v_lshl_add_u64 v[14:15], v[14:15], 0, v[20:21]
	global_load_ushort v17, v[14:15], off
	v_or_b32_e32 v20, 16, v16
	v_ashrrev_i32_e32 v21, 31, v20
	v_lshlrev_b64 v[20:21], 8, v[20:21]
	v_lshl_add_u64 v[32:33], v[18:19], 0, v[20:21]
	s_waitcnt vmcnt(0)
	v_lshlrev_b32_e32 v17, 16, v17
	v_add_f32_e32 v17, v23, v17
	v_cvt_pk_bf16_f32 v17, v17, s0
	global_store_short v[14:15], v17, off
	global_load_dwordx4 v[20:23], v[32:33], off offset:16
	global_load_dwordx4 v[24:27], v[32:33], off
	global_load_dwordx4 v[28:31], v[32:33], off offset:144
	s_nop 0
	global_load_dwordx4 v[32:35], v[32:33], off offset:128
	s_waitcnt vmcnt(2)
; __device__ __forceinline__ float bf2f(bf16_t v) { return __uint_as_float(((unsigned)v) << 16); }
; __device__ __forceinline__ bf16_t f2bf(float f) { return (bf16_t)(pack2(f, 0.f) & 0xffffu); }
; #define MFMA(a, b, c) __builtin_amdgcn_mfma_f32_16x16x32_bf16(a, b, c, 0, 0, 0)
; __device__ __forceinline__ void rwkv_fix_tile(const Params& p, int tile) {
;     ...
;   for (int nt = 0; nt < 4; ++nt) {
;     const float* sp = p.SMID + ((size_t)(dbh * 64 + nt * 16 + fr)) * 64 + fq * 8;
;     const float4 f0 = *(const float4*)sp, f1 = *(const float4*)(sp + 4), f2 = *(const float4*)(sp + 32), f3 = *(const float4*)(sp + 36);
;     union { unsigned u[4]; bf16x8 v; } b0, b1;
;     b0.u[0] = pack2(f0.x, f0.y); b0.u[1] = pack2(f0.z, f0.w); b0.u[2] = pack2(f1.x, f1.y); b0.u[3] = pack2(f1.z, f1.w);
;     b1.u[0] = pack2(f2.x, f2.y); b1.u[1] = pack2(f2.z, f2.w); b1.u[2] = pack2(f3.x, f3.y); b1.u[3] = pack2(f3.z, f3.w);
;     f32x4 acc = (f32x4){0.f, 0.f, 0.f, 0.f};
;     acc = MFMA(a0, b0.v, acc);
;     acc = MFMA(a1, b1.v, acc);
; #pragma unroll
;     for (int j = 0; j < 4; ++j) {
;       const int st = CSPLIT * 32 + s0 + fq * 4 + j;
;       const int pp = (d == 0) ? st : ((st < 256) ? 255 - st : 4607 - st);
;       bf16_t* yp = p.yR + ((size_t)d * TOK + rowbase + pp) * 256 + h * 64 + nt * 16 + fr;
;       *yp = f2bf(bf2f(*yp) + acc[j]);
;     }
;   }
; }
; __device__ __forceinline__ void phase_rwkvfix(const Params& p) {
;   for (int t = blockIdx.x; t < 32 * (NSEG1 / 64); t += gridDim.x) rwkv_fix_tile(p, t);
	v_cvt_pk_bf16_f32 v24, v24, v25
	global_load_ushort v17, v[8:9], off offset:32
	v_cvt_pk_bf16_f32 v25, v26, v27
	v_cvt_pk_bf16_f32 v26, v20, v21
	v_cvt_pk_bf16_f32 v27, v22, v23
	s_waitcnt vmcnt(1)
	v_cvt_pk_bf16_f32 v20, v32, v33
	v_cvt_pk_bf16_f32 v21, v34, v35
	v_mfma_f32_16x16x32_bf16 v[24:27], v[0:3], v[24:27], 0
	v_cvt_pk_bf16_f32 v22, v28, v29
	v_cvt_pk_bf16_f32 v23, v30, v31
	s_waitcnt vmcnt(0)
	v_lshlrev_b32_e32 v17, 16, v17
	v_mfma_f32_16x16x32_bf16 v[20:23], v[4:7], v[20:23], v[24:27]
	s_nop 7
	v_add_f32_e32 v17, v20, v17
	v_cvt_pk_bf16_f32 v17, v17, s0
	global_store_short v[8:9], v17, off offset:32
	global_load_ushort v17, v[10:11], off offset:32
	v_or_b32_e32 v20, 32, v16
	v_or_b32_e32 v16, 48, v16
	s_waitcnt vmcnt(0)
	v_lshlrev_b32_e32 v17, 16, v17
	v_add_f32_e32 v17, v21, v17
	v_cvt_pk_bf16_f32 v17, v17, s0
	global_store_short v[10:11], v17, off offset:32
	global_load_ushort v17, v[12:13], off offset:32
	v_ashrrev_i32_e32 v21, 31, v20
	v_lshlrev_b64 v[20:21], 8, v[20:21]
	v_lshl_add_u64 v[32:33], v[18:19], 0, v[20:21]
	s_waitcnt vmcnt(0)
	v_lshlrev_b32_e32 v17, 16, v17
	v_add_f32_e32 v17, v22, v17
	v_cvt_pk_bf16_f32 v17, v17, s0
	global_store_short v[12:13], v17, off offset:32
	global_load_ushort v17, v[14:15], off offset:32
	s_waitcnt vmcnt(0)
	v_lshlrev_b32_e32 v17, 16, v17
	v_add_f32_e32 v17, v23, v17
	v_cvt_pk_bf16_f32 v17, v17, s0
	global_store_short v[14:15], v17, off offset:32
	global_load_dwordx4 v[20:23], v[32:33], off offset:16
	global_load_dwordx4 v[24:27], v[32:33], off
	global_load_dwordx4 v[28:31], v[32:33], off offset:144
	s_nop 0
	global_load_dwordx4 v[32:35], v[32:33], off offset:128
	s_waitcnt vmcnt(2)
	v_cvt_pk_bf16_f32 v24, v24, v25
	global_load_ushort v17, v[8:9], off offset:64
	v_cvt_pk_bf16_f32 v25, v26, v27
	v_cvt_pk_bf16_f32 v26, v20, v21
	v_cvt_pk_bf16_f32 v27, v22, v23
	s_waitcnt vmcnt(1)
	v_cvt_pk_bf16_f32 v20, v32, v33
	v_cvt_pk_bf16_f32 v21, v34, v35
	v_mfma_f32_16x16x32_bf16 v[24:27], v[0:3], v[24:27], 0
	v_cvt_pk_bf16_f32 v22, v28, v29
	v_cvt_pk_bf16_f32 v23, v30, v31
	s_waitcnt vmcnt(0)
	v_lshlrev_b32_e32 v17, 16, v17
	v_mfma_f32_16x16x32_bf16 v[20:23], v[4:7], v[20:23], v[24:27]
	s_nop 7
	v_add_f32_e32 v17, v20, v17
	v_cvt_pk_bf16_f32 v17, v17, s0
	global_store_short v[8:9], v17, off offset:64
	global_load_ushort v17, v[10:11], off offset:64
	s_waitcnt vmcnt(0)
	v_lshlrev_b32_e32 v17, 16, v17
	v_add_f32_e32 v17, v21, v17
	v_cvt_pk_bf16_f32 v17, v17, s0
	global_store_short v[10:11], v17, off offset:64
	global_load_ushort v17, v[12:13], off offset:64
	s_waitcnt vmcnt(0)
	v_lshlrev_b32_e32 v17, 16, v17
	v_add_f32_e32 v17, v22, v17
	v_cvt_pk_bf16_f32 v17, v17, s0
	global_store_short v[12:13], v17, off offset:64
	global_load_ushort v17, v[14:15], off offset:64
	s_waitcnt vmcnt(0)
	v_lshlrev_b32_e32 v17, 16, v17
	v_add_f32_e32 v17, v23, v17
	v_cvt_pk_bf16_f32 v17, v17, s0
	global_store_short v[14:15], v17, off offset:64
	v_ashrrev_i32_e32 v17, 31, v16
	v_lshlrev_b64 v[16:17], 8, v[16:17]
	v_lshl_add_u64 v[28:29], v[18:19], 0, v[16:17]
	global_load_dwordx4 v[16:19], v[28:29], off offset:16
	global_load_dwordx4 v[20:23], v[28:29], off
	global_load_dwordx4 v[24:27], v[28:29], off offset:144
	s_nop 0
	global_load_dwordx4 v[28:31], v[28:29], off offset:128
	s_waitcnt vmcnt(2)
	v_cvt_pk_bf16_f32 v20, v20, v21
	v_cvt_pk_bf16_f32 v21, v22, v23
	v_cvt_pk_bf16_f32 v22, v16, v17
	v_cvt_pk_bf16_f32 v23, v18, v19
	s_waitcnt vmcnt(0)
	v_cvt_pk_bf16_f32 v16, v28, v29
	v_cvt_pk_bf16_f32 v17, v30, v31
	v_mfma_f32_16x16x32_bf16 v[0:3], v[0:3], v[20:23], 0
	v_cvt_pk_bf16_f32 v18, v24, v25
	v_cvt_pk_bf16_f32 v19, v26, v27
	s_nop 1
	v_mfma_f32_16x16x32_bf16 v[0:3], v[4:7], v[16:19], v[0:3]
	global_load_ushort v4, v[8:9], off offset:96
	s_waitcnt vmcnt(0)
	v_lshlrev_b32_e32 v4, 16, v4
	s_nop 4
	v_add_f32_e32 v0, v0, v4
	v_cvt_pk_bf16_f32 v0, v0, s0
	global_store_short v[8:9], v0, off offset:96
	global_load_ushort v0, v[10:11], off offset:96
	s_waitcnt vmcnt(0)
	v_lshlrev_b32_e32 v0, 16, v0
	v_add_f32_e32 v0, v1, v0
	v_cvt_pk_bf16_f32 v0, v0, s0
	global_store_short v[10:11], v0, off offset:96
	global_load_ushort v0, v[12:13], off offset:96
	s_waitcnt vmcnt(0)
	v_lshlrev_b32_e32 v0, 16, v0
	v_add_f32_e32 v0, v2, v0
	v_cvt_pk_bf16_f32 v0, v0, s0
	global_store_short v[12:13], v0, off offset:96
	global_load_ushort v0, v[14:15], off offset:96
	s_waitcnt vmcnt(0)
	v_lshlrev_b32_e32 v0, 16, v0
	v_add_f32_e32 v0, v3, v0
	v_cvt_pk_bf16_f32 v0, v0, s0
	global_store_short v[14:15], v0, off offset:96
	s_load_dword s28, s[2:3], 0x0
	s_waitcnt lgkmcnt(0)
	s_add_i32 s46, s28, s46
	s_cmpk_gt_i32 s46, 0x2ff
	s_cbranch_scc0 .LBB0_123

; template <bool DUAL>
; __device__ __forceinline__ void rwkv_tile(const Params& p, int l, int tile, unsigned char* smem) {
;     ...
;   const int lc = (tid & 15) * 4;
;   const float* mu0 = p.rwkv_mu + (size_t)(l * 2 + 0) * 1024 + h * 64 + lc;
;   const float* mu1 = p.rwkv_mu + (size_t)(l * 2 + 1) * 1024 + h * 64 + lc;
;   const float4 m0r = *(const float4*)mu0, m1r = *(const float4*)mu1;
;   const float4 m0k = *(const float4*)(mu0 + 256), m1k = *(const float4*)(mu1 + 256);
;   const float4 m0v = *(const float4*)(mu0 + 512), m1v = *(const float4*)(mu1 + 512);
;   const float4 ka4 = *(const float4*)(p.rwkv_k_a + ld2 * 256 + h * 64 + lc);
;   v2f sA = {0.f, 0.f}, sB = {0.f, 0.f};
;   v2f iA = {(row == c0) ? 1.f : 0.f, (row == c0 + 1) ? 1.f : 0.f}, iB = {(row == c0 + 2) ? 1.f : 0.f, (row == c0 + 3) ? 1.f : 0.f};
;   const int pcc = tid % 24, prow = tid / 24;
;   const bool pact = tid < 240;
;   const bf16_t* rbase_g = p.PR + rowbase * 1024 + (pcc >> 3) * 256 + h * 64 + (pcc & 7) * 8;
;   const bf16_t* pbase_g = p.PRE + (size_t)(pcc >> 3) * PRE_ARR + (rowbase * 2 + d) * 256 + h * 64 + (pcc & 7) * 8;
;   uint4 pf0, pf1, pf2, pf3, pg0, pg1, pg2, pg3;
.LBB0_267:
	s_lshl_b32 s59, s92, 4
	s_bfe_u32 s57, s92, 0x10006
	s_and_b32 s48, s59, 0xc0
	s_bfe_u32 s56, s92, 0x20004
	s_or_b32 s28, s57, s84
	s_lshl_b32 s49, s48, 2
	s_add_u32 s42, s85, s49
	s_addc_u32 s43, s77, 0
	s_add_u32 s44, s78, s49
	s_addc_u32 s45, s79, 0
	s_lshl_b32 s46, s28, 8
	s_ashr_i32 s47, s46, 31
	v_mov_b32_e32 v61, v189
	s_lshl_b64 s[46:47], s[46:47], 2
	v_readlane_b32 s60, v251, 16
	v_readlane_b32 s61, v251, 17
	v_lshlrev_b32_e32 v0, 2, v61
	s_add_u32 s28, s60, s46
	v_and_b32_e32 v60, 60, v0
	s_addc_u32 s47, s61, s47
	v_lshlrev_b32_e32 v24, 2, v60
	s_add_u32 s46, s28, s49
	global_load_dwordx4 v[0:3], v24, s[44:45]
	global_load_dwordx4 v[4:7], v24, s[42:43] offset:2048
	s_addc_u32 s47, s47, 0
	global_load_dwordx4 v[8:11], v24, s[42:43]
	global_load_dwordx4 v[12:15], v24, s[42:43] offset:1024
	global_load_dwordx4 v[16:19], v24, s[44:45] offset:2048
	global_load_dwordx4 v[20:23], v24, s[44:45] offset:1024
	s_nop 0
	global_load_dwordx4 v[24:27], v24, s[46:47]
	s_mov_b32 s0, 0x2aaaaaab
	s_waitcnt vmcnt(7)
	v_mul_hi_i32 v28, v61, s0
	v_lshrrev_b32_e32 v29, 31, v28
	v_ashrrev_i32_e32 v28, 2, v28
	s_movk_i32 s0, 0xef
	v_add_u32_e32 v97, v28, v29
	v_cmp_lt_i32_e32 vcc, s0, v61
	s_movk_i32 s0, 0xf0
	s_mul_i32 s58, s56, 0x1100
	v_mul_lo_u32 v28, v97, 24
	v_cmp_gt_i32_e64 s[42:43], s0, v61
	v_readlane_b32 s0, v251, 48
	v_sub_u32_e32 v30, v61, v28
	s_lshl_b32 s28, s58, 11
	v_readlane_b32 s10, v251, 58
	v_readlane_b32 s11, v251, 59
	s_add_u32 s44, s10, s28
	v_ashrrev_i32_e32 v46, 3, v30
	s_addc_u32 s45, s11, 0
	v_lshlrev_b32_e32 v28, 8, v46
	s_lshl_b32 s50, s48, 1
	v_ashrrev_i32_e32 v29, 31, v28
	s_cmp_eq_u32 s57, 0
	v_lshl_add_u64 v[28:29], v[28:29], 1, s[44:45]
	s_cselect_b64 s[44:45], -1, 0
	s_and_b64 s[46:47], s[44:45], exec
	s_movk_i32 s0, 0xb00
	v_lshlrev_b32_e32 v62, 3, v30
	s_cselect_b32 s54, s0, 0x6e0
	s_mov_b32 s51, s29
	v_and_b32_e32 v30, 56, v62
	s_add_i32 s28, s54, -1
	v_lshl_add_u64 v[28:29], v[28:29], 0, s[50:51]
	v_lshlrev_b32_e32 v44, 1, v30
	v_mov_b32_e32 v45, v164
	v_add_u32_e32 v30, s28, v97
	v_lshl_add_u64 v[80:81], v[28:29], 0, v[44:45]
	v_add_u32_e32 v28, 0xffffff00, v30
	v_cmp_gt_u32_e64 s[46:47], s31, v28
	v_mov_b32_e32 v28, v164
	v_mov_b32_e32 v29, v164
	s_and_b64 s[48:49], s[42:43], s[46:47]
	v_mov_b64_e32 v[32:33], v[28:29]
	v_mov_b64_e32 v[34:35], v[28:29]
	v_readlane_b32 s62, v251, 18
	v_readlane_b32 s63, v251, 19
	v_readlane_b32 s64, v251, 20
	v_readlane_b32 s65, v251, 21
	v_readlane_b32 s66, v251, 22
	v_readlane_b32 s67, v251, 23
	v_readlane_b32 s68, v251, 24
	v_readlane_b32 s69, v251, 25
	v_readlane_b32 s70, v251, 26
	v_readlane_b32 s71, v251, 27
	v_readlane_b32 s72, v251, 28
	v_readlane_b32 s73, v251, 29
	v_readlane_b32 s74, v251, 30
	v_readlane_b32 s75, v251, 31
	v_readlane_b32 s1, v251, 49
	v_readlane_b32 s2, v251, 50
	v_readlane_b32 s3, v251, 51
	v_readlane_b32 s4, v251, 52
	v_readlane_b32 s5, v251, 53
	v_readlane_b32 s6, v251, 54
	v_readlane_b32 s7, v251, 55
	v_readlane_b32 s8, v251, 56
	v_readlane_b32 s9, v251, 57
	v_readlane_b32 s12, v251, 60
	v_readlane_b32 s13, v251, 61
	v_readlane_b32 s14, v251, 62
	v_readlane_b32 s15, v251, 63
	s_and_saveexec_b64 s[46:47], s[48:49]
	s_cbranch_execz .LBB0_269
	v_lshlrev_b32_e32 v30, 11, v30
	v_mov_b32_e32 v31, v164
	v_lshl_add_u64 v[30:31], v[80:81], 0, v[30:31]
	global_load_dwordx4 v[32:35], v[30:31], off

; __device__ __forceinline__ int launder(int x) { asm volatile("" : "+v"(x)); return x; }
; template <bool DUAL>
; __device__ __forceinline__ void rwkv_tile(const Params& p, int l, int tile, unsigned char* smem) {
;     ...
;   const int tid = launder(threadIdx.x), lane = tid & 63, w = tid >> 6, fr = lane & 15, fq = lane >> 4;
;   const int row = rg * 16 + w * 4 + fq;
;   const int c0 = fr * 4;
;   const int ld2 = l * 2 + d;
;   const size_t rowbase = (size_t)b * TPB;
;   const int lc = (tid & 15) * 4;
;   const float* mu0 = p.rwkv_mu + (size_t)(l * 2 + 0) * 1024 + h * 64 + lc;
;   const float* mu1 = p.rwkv_mu + (size_t)(l * 2 + 1) * 1024 + h * 64 + lc;
;   const float4 m0r = *(const float4*)mu0, m1r = *(const float4*)mu1;
;   const float4 m0k = *(const float4*)(mu0 + 256), m1k = *(const float4*)(mu1 + 256);
;   const float4 m0v = *(const float4*)(mu0 + 512), m1v = *(const float4*)(mu1 + 512);
;   const float4 ka4 = *(const float4*)(p.rwkv_k_a + ld2 * 256 + h * 64 + lc);
;   v2f sA = {0.f, 0.f}, sB = {0.f, 0.f};
;   v2f iA = {(row == c0) ? 1.f : 0.f, (row == c0 + 1) ? 1.f : 0.f}, iB = {(row == c0 + 2) ? 1.f : 0.f, (row == c0 + 3) ? 1.f : 0.f};
;   const int pcc = tid % 24, prow = tid / 24;
;   const bool pact = tid < 240;
;   const bf16_t* rbase_g = p.PR + rowbase * 1024 + (pcc >> 3) * 256 + h * 64 + (pcc & 7) * 8;
;   const bf16_t* pbase_g = p.PRE + (size_t)(pcc >> 3) * PRE_ARR + (rowbase * 2 + d) * 256 + h * 64 + (pcc & 7) * 8;
;   uint4 pf0, pf1, pf2, pf3, pg0, pg1, pg2, pg3;
.LBB0_291:
	s_or_b64 exec, exec, s[52:53]
	v_and_b32_e32 v101, 15, v61
	v_bfe_u32 v68, v61, 4, 2
	v_ashrrev_i32_e32 v61, 4, v61
	s_and_b32 s28, s59, 48
	v_and_b32_e32 v69, -4, v61
	v_add_u32_e32 v66, s28, v69
	v_or_b32_e32 v66, v66, v68
	v_lshlrev_b32_e32 v67, 2, v101
	v_lshl_add_u32 v62, v62, 1, 0
	v_cmp_eq_u32_e32 vcc, v66, v67
	v_or_b32_e32 v70, 1, v67
	v_lshl_add_u32 v105, v64, 1, v62
	v_lshl_add_u32 v106, v65, 1, v62
	v_add_u32_e32 v64, 1, v61
	v_sub_u32_e32 v65, 32, v61
	v_cndmask_b32_e64 v86, 0, 1.0, vcc
	v_cmp_eq_u32_e32 vcc, v66, v70
	v_or_b32_e32 v70, 2, v67
	v_lshlrev_b32_e32 v60, 1, v60
	s_movk_i32 s0, 0x180
	v_cndmask_b32_e64 v64, v65, v64, s[44:45]
	v_cndmask_b32_e64 v87, 0, 1.0, vcc
	v_cmp_eq_u32_e32 vcc, v66, v70
	v_add_u32_e32 v70, 0, v60
	v_mul_lo_u32 v64, v64, s0
	s_movk_i32 s1, 0x600
	v_add_u32_e32 v107, v70, v64
	v_add3_u32 v111, 0, v64, v60
	v_mul_lo_u32 v64, v61, s1
	v_add_u32_e32 v65, 17, v61
	v_sub_u32_e32 v61, 16, v61
	s_mul_i32 s28, s57, 0x4400
	s_lshl_b32 s51, s57, 2
	v_cndmask_b32_e64 v61, v61, v65, s[44:45]
	s_add_i32 s28, s28, s58
	s_or_b32 s51, s51, s56
	v_lshl_add_u32 v104, v63, 1, v62
	v_mul_lo_u32 v63, v100, s0
	v_mul_lo_u32 v61, v61, s0
	v_readlane_b32 s0, v252, 0
	v_readlane_b32 s1, v252, 1
	s_add_u32 s52, s0, s50
	v_or_b32_e32 v67, 3, v67
	v_readlane_b32 s10, v252, 10
	s_addc_u32 s53, s1, 0
	v_cndmask_b32_e64 v90, 0, 1.0, vcc
	v_cmp_eq_u32_e32 vcc, v66, v67
	v_ashrrev_i32_e32 v67, 31, v66
	v_readlane_b32 s11, v252, 11
	s_add_u32 s50, s10, s50
	v_add_u32_e32 v71, v70, v60
	s_mul_i32 s54, s51, 0x600
	v_add_u32_e32 v112, v70, v61
	v_add3_u32 v116, 0, v61, v60
	v_lshlrev_b64 v[60:61], 1, v[66:67]
	s_addc_u32 s51, s11, 0
	v_lshl_add_u64 v[84:85], s[52:53], 0, v[60:61]
	v_lshl_add_u64 v[88:89], s[50:51], 0, v[60:61]
	v_add3_u32 v60, s93, v69, v68
	v_readlane_b32 s0, v255, 26
	v_lshlrev_b32_e32 v72, 4, v101
	v_mov_b32_e32 v165, v164
	v_lshl_add_u32 v117, v60, 2, s0
	v_readlane_b32 s0, v255, 27
	v_cndmask_b32_e64 v91, 0, 1.0, vcc
	v_add_u32_e32 v102, 0, v72
	v_lshl_add_u32 v103, v66, 2, 0
	v_add_u32_e32 v108, 0xfffffe80, v107
	v_add_u32_e32 v109, 0xffffff00, v107
	v_add_u32_e32 v110, 0xffffff80, v107
	v_add_u32_e32 v113, 0xfffffe80, v112
	v_add_u32_e32 v114, 0xffffff00, v112
	v_add_u32_e32 v115, 0xffffff80, v112
	v_add_u32_e32 v118, s0, v72
	s_movk_i32 s55, 0x58
	v_add_u32_e32 v119, v71, v64
	v_add_u32_e32 v120, v62, v63
	v_mov_b64_e32 v[94:95], v[164:165]
	v_mov_b64_e32 v[92:93], v[164:165]
	s_waitcnt lgkmcnt(0)
	s_barrier
	v_readlane_b32 s2, v252, 2
	v_readlane_b32 s3, v252, 3
	v_readlane_b32 s4, v252, 4
	v_readlane_b32 s5, v252, 5
	v_readlane_b32 s6, v252, 6
	v_readlane_b32 s7, v252, 7
	v_readlane_b32 s8, v252, 8
	v_readlane_b32 s9, v252, 9
	v_readlane_b32 s12, v252, 12
	v_readlane_b32 s13, v252, 13
	v_readlane_b32 s14, v252, 14
	v_readlane_b32 s15, v252, 15
	s_branch .LBB0_293

; template <bool DUAL>
; __device__ __forceinline__ void rwkv_tile(const Params& p, int l, int tile, unsigned char* smem) {
;     ...
;     int plo, slo, shi;
;     RW_GEOM(cix, plo, slo, shi);
;     ...
;       const float* rp = rec + c0;
;       const float* vp = rec + 320 + row;
;       float4 w4 = *(const float4*)(rp), kk4 = *(const float4*)(rp + 64), kb4 = *(const float4*)(rp + 128);
;       float4 kd4 = *(const float4*)(rp + 192), r4 = *(const float4*)(rp + 256);
;       float v = vp[0];
.LBB0_311:
	ds_read_b128 v[60:63], v102 offset:25344
	ds_read_b128 v[76:79], v102 offset:25600
	ds_read_b128 v[64:67], v102 offset:25856
	ds_read_b128 v[72:75], v102 offset:26112
	ds_read_b128 v[68:71], v102 offset:26368
	ds_read_b32 v96, v103 offset:26624
	s_lshl_b32 s57, s55, 5
	s_sub_i32 s55, 0x11e0, s57
	s_and_b64 s[52:53], s[44:45], exec
	s_cselect_b32 s55, s57, s55
	s_addk_i32 s57, 0xf500
	s_add_i32 s55, s55, -1
	s_ashr_i32 s52, s57, 31
	s_add_u32 s57, s57, s54
	s_addc_u32 s58, s52, 0
	v_mov_b32_e32 v123, 0
	s_mov_b32 s59, 0
	v_mov_b32_e32 v121, v118
	v_mov_b32_e32 v122, v117
	v_mov_b32_e32 v124, 0

; __device__ __forceinline__ int launder(int x) { asm volatile("" : "+v"(x)); return x; }
; template <bool DUAL>
; __device__ __forceinline__ void rwkv_tile(const Params& p, int l, int tile, unsigned char* smem) {
;   const int part = tile >> 7;
;   const int rg = tile & 3, h = (tile >> 2) & 3, b = (tile >> 4) & 3, d = (tile >> 6) & 1;
;   const int cbeg = (part == 0) ? 0 : CSPLIT, cend = (part == 0) ? CSPLIT : 136;
;   bf16_t* raw = (bf16_t*)smem;
;   bf16_t* pre = raw + 34 * 192;
;   float* rec = (float*)(smem + 13056 + 12288);
;   const int tid = launder(threadIdx.x), lane = tid & 63, w = tid >> 6, fr = lane & 15, fq = lane >> 4;
;   const int row = rg * 16 + w * 4 + fq;
;   const int c0 = fr * 4;
;   const int ld2 = l * 2 + d;
;   const size_t rowbase = (size_t)b * TPB;
;   const int lc = (tid & 15) * 4;
;   const float* mu0 = p.rwkv_mu + (size_t)(l * 2 + 0) * 1024 + h * 64 + lc;
;   const float* mu1 = p.rwkv_mu + (size_t)(l * 2 + 1) * 1024 + h * 64 + lc;
;   const float4 m0r = *(const float4*)mu0, m1r = *(const float4*)mu1;
;   const float4 m0k = *(const float4*)(mu0 + 256), m1k = *(const float4*)(mu1 + 256);
;   const float4 m0v = *(const float4*)(mu0 + 512), m1v = *(const float4*)(mu1 + 512);
;   const float4 ka4 = *(const float4*)(p.rwkv_k_a + ld2 * 256 + h * 64 + lc);
;   v2f sA = {0.f, 0.f}, sB = {0.f, 0.f};
;   v2f iA = {(row == c0) ? 1.f : 0.f, (row == c0 + 1) ? 1.f : 0.f}, iB = {(row == c0 + 2) ? 1.f : 0.f, (row == c0 + 3) ? 1.f : 0.f};
;   const int pcc = tid % 24, prow = tid / 24;
;   const bool pact = tid < 240;
;   const bf16_t* rbase_g = p.PR + rowbase * 1024 + (pcc >> 3) * 256 + h * 64 + (pcc & 7) * 8;
;   const bf16_t* pbase_g = p.PRE + (size_t)(pcc >> 3) * PRE_ARR + (rowbase * 2 + d) * 256 + h * 64 + (pcc & 7) * 8;
;   uint4 pf0, pf1, pf2, pf3, pg0, pg1, pg2, pg3;
.LBB0_375:
	s_andn2_b64 vcc, exec, s[42:43]
	s_cbranch_vccnz .LBB0_163
	s_bfe_u32 s68, s92, 0x20002
	s_bfe_u32 s73, s92, 0x10006
	s_bfe_u32 s69, s92, 0x20004
	s_or_b32 s28, s73, s84
	s_lshl_b32 s48, s68, 8
	s_add_u32 s42, s85, s48
	s_addc_u32 s43, s77, 0
	s_add_u32 s44, s78, s48
	s_addc_u32 s45, s79, 0
	s_lshl_b32 s46, s28, 8
	s_ashr_i32 s47, s46, 31
	s_lshl_b64 s[46:47], s[46:47], 2
	v_readlane_b32 s52, v251, 16
	v_mov_b32_e32 v61, v189
	v_readlane_b32 s53, v251, 17
	s_add_u32 s28, s52, s46
	s_addc_u32 s47, s53, s47
	v_lshlrev_b32_e32 v0, 2, v61
	v_and_b32_e32 v60, 60, v0
	s_add_u32 s46, s28, s48
	v_lshlrev_b32_e32 v24, 2, v60
	s_addc_u32 s47, s47, 0
	global_load_dwordx4 v[0:3], v24, s[44:45]
	global_load_dwordx4 v[4:7], v24, s[42:43] offset:2048
	global_load_dwordx4 v[8:11], v24, s[42:43]
	global_load_dwordx4 v[12:15], v24, s[42:43] offset:1024
	global_load_dwordx4 v[16:19], v24, s[44:45] offset:2048
	global_load_dwordx4 v[20:23], v24, s[44:45] offset:1024
	s_nop 0
	global_load_dwordx4 v[24:27], v24, s[46:47]
	v_readlane_b32 s0, v251, 48
	s_mov_b32 s0, 0x2aaaaaab
	s_mul_i32 s94, s69, 0x1100
	s_waitcnt vmcnt(7)
	v_mul_hi_i32 v28, v61, s0
	s_lshl_b32 s28, s94, 11
	v_readlane_b32 s10, v251, 58
	v_lshrrev_b32_e32 v29, 31, v28
	v_ashrrev_i32_e32 v28, 2, v28
	v_readlane_b32 s11, v251, 59
	s_add_u32 s44, s10, s28
	v_add_u32_e32 v93, v28, v29
	s_addc_u32 s45, s11, 0
	s_lshl_b32 s28, s68, 7
	v_mul_lo_u32 v28, v93, 24
	v_readlane_b32 s54, v251, 18
	v_readlane_b32 s55, v251, 19
	s_cmpk_lt_u32 s92, 0x80
	v_sub_u32_e32 v30, v61, v28
	s_cselect_b64 s[54:55], -1, 0
	s_movk_i32 s0, 0xef
	v_ashrrev_i32_e32 v48, 3, v30
	s_and_b64 s[42:43], s[54:55], exec
	v_cmp_lt_i32_e32 vcc, s0, v61
	s_movk_i32 s0, 0xf0
	v_lshlrev_b32_e32 v28, 8, v48
	v_cmp_gt_i32_e64 s[42:43], s0, v61
	v_ashrrev_i32_e32 v29, 31, v28
	s_movk_i32 s0, 0x11e0
	s_cselect_b32 s70, 0, 0x58
	v_lshl_add_u64 v[28:29], v[28:29], 1, s[44:45]
	s_cselect_b32 s44, 0xe0, s0
	s_movk_i32 s0, 0x10ff
	v_lshl_add_u64 v[28:29], v[28:29], 0, s[28:29]
	s_cselect_b32 s28, 0xff, s0
	s_cselect_b32 s50, 0, 0x100
	s_lshl_b32 s48, s70, 5
	s_sub_i32 s49, s44, s48
	s_cmp_eq_u32 s73, 0
	s_cselect_b64 s[44:45], -1, 0
	v_readlane_b32 s58, v251, 22
	s_and_b64 s[46:47], s[44:45], exec
	v_lshlrev_b32_e32 v62, 3, v30
	s_cselect_b32 s58, s48, s49
	v_and_b32_e32 v30, 56, v62
	s_add_i32 s51, s58, -1
	v_lshlrev_b32_e32 v44, 1, v30
	v_add_u32_e32 v30, s51, v93
	v_mov_b32_e32 v45, v164
	v_cmp_le_i32_e64 s[46:47], s50, v30
	v_cmp_ge_i32_e64 s[48:49], s28, v30
	v_lshl_add_u64 v[84:85], v[28:29], 0, v[44:45]
	s_and_b64 s[46:47], s[46:47], s[48:49]
	v_mov_b32_e32 v28, v164
	v_mov_b32_e32 v29, v164
	s_and_b64 s[48:49], s[42:43], s[46:47]
	v_mov_b64_e32 v[32:33], v[28:29]
	v_mov_b64_e32 v[34:35], v[28:29]
	v_readlane_b32 s56, v251, 20
	v_readlane_b32 s57, v251, 21
	v_readlane_b32 s59, v251, 23
	v_readlane_b32 s60, v251, 24
	v_readlane_b32 s61, v251, 25
	v_readlane_b32 s62, v251, 26
	v_readlane_b32 s63, v251, 27
	v_readlane_b32 s64, v251, 28
	v_readlane_b32 s65, v251, 29
	v_readlane_b32 s66, v251, 30
	v_readlane_b32 s67, v251, 31
	v_readlane_b32 s1, v251, 49
	v_readlane_b32 s2, v251, 50
	v_readlane_b32 s3, v251, 51
	v_readlane_b32 s4, v251, 52
	v_readlane_b32 s5, v251, 53
	v_readlane_b32 s6, v251, 54
	v_readlane_b32 s7, v251, 55
	v_readlane_b32 s8, v251, 56
	v_readlane_b32 s9, v251, 57
	v_readlane_b32 s12, v251, 60
	v_readlane_b32 s13, v251, 61
	v_readlane_b32 s14, v251, 62
	v_readlane_b32 s15, v251, 63
	s_and_saveexec_b64 s[46:47], s[48:49]
	s_cbranch_execz .LBB0_378
	v_mov_b32_e32 v31, v164
	v_lshlrev_b64 v[30:31], 11, v[30:31]
	v_lshl_add_u64 v[30:31], v[84:85], 0, v[30:31]
	global_load_dwordx4 v[32:35], v[30:31], off

; __device__ __forceinline__ int launder(int x) { asm volatile("" : "+v"(x)); return x; }
; template <bool DUAL>
; __device__ __forceinline__ void rwkv_tile(const Params& p, int l, int tile, unsigned char* smem) {
;     ...
;   const int cbeg = (part == 0) ? 0 : CSPLIT, cend = (part == 0) ? CSPLIT : 136;
;   bf16_t* raw = (bf16_t*)smem;
;   bf16_t* pre = raw + 34 * 192;
;   float* rec = (float*)(smem + 13056 + 12288);
;   const int tid = launder(threadIdx.x), lane = tid & 63, w = tid >> 6, fr = lane & 15, fq = lane >> 4;
;   const int row = rg * 16 + w * 4 + fq;
;   const int c0 = fr * 4;
;   const int ld2 = l * 2 + d;
;   const size_t rowbase = (size_t)b * TPB;
;   const int lc = (tid & 15) * 4;
;   const float* mu0 = p.rwkv_mu + (size_t)(l * 2 + 0) * 1024 + h * 64 + lc;
;   const float* mu1 = p.rwkv_mu + (size_t)(l * 2 + 1) * 1024 + h * 64 + lc;
;   const float4 m0r = *(const float4*)mu0, m1r = *(const float4*)mu1;
;   const float4 m0k = *(const float4*)(mu0 + 256), m1k = *(const float4*)(mu1 + 256);
;   const float4 m0v = *(const float4*)(mu0 + 512), m1v = *(const float4*)(mu1 + 512);
;   const float4 ka4 = *(const float4*)(p.rwkv_k_a + ld2 * 256 + h * 64 + lc);
;   v2f sA = {0.f, 0.f}, sB = {0.f, 0.f};
;   v2f iA = {(row == c0) ? 1.f : 0.f, (row == c0 + 1) ? 1.f : 0.f}, iB = {(row == c0 + 2) ? 1.f : 0.f, (row == c0 + 3) ? 1.f : 0.f};
;   const int pcc = tid % 24, prow = tid / 24;
;   const bool pact = tid < 240;
;   const bf16_t* rbase_g = p.PR + rowbase * 1024 + (pcc >> 3) * 256 + h * 64 + (pcc & 7) * 8;
.LBB0_400:
	s_or_b64 exec, exec, s[56:57]
	s_lshr_b32 s71, s92, 6
	s_and_b64 s[56:57], s[54:55], exec
	s_movk_i32 s0, 0x88
	s_cselect_b32 s72, 0x58, s0
	v_and_b32_e32 v98, 15, v61
	v_bfe_u32 v66, v61, 4, 2
	s_lshl_b32 s28, s92, 4
	v_ashrrev_i32_e32 v61, 4, v61
	v_lshl_add_u32 v62, v62, 1, 0
	s_and_b32 s28, s28, 48
	v_and_b32_e32 v67, -4, v61
	v_lshl_add_u32 v102, v64, 1, v62
	v_lshl_add_u32 v103, v65, 1, v62
	v_add_u32_e32 v64, 1, v61
	v_sub_u32_e32 v65, 32, v61
	v_add_u32_e32 v68, s28, v67
	v_lshlrev_b32_e32 v60, 1, v60
	s_movk_i32 s0, 0x180
	v_cndmask_b32_e64 v64, v65, v64, s[44:45]
	v_or_b32_e32 v88, v68, v66
	v_add_u32_e32 v68, 0, v60
	v_mul_lo_u32 v64, v64, s0
	s_movk_i32 s1, 0x600
	v_add_u32_e32 v104, v68, v64
	v_add3_u32 v108, 0, v64, v60
	v_mul_lo_u32 v64, v61, s1
	v_add_u32_e32 v65, 17, v61
	v_sub_u32_e32 v61, 16, v61
	s_mul_i32 s28, s73, 0x4400
	v_cndmask_b32_e64 v61, v61, v65, s[44:45]
	s_add_i32 s28, s28, s94
	v_lshl_add_u32 v101, v63, 1, v62
	v_mul_lo_u32 v63, v96, s0
	v_mul_lo_u32 v61, v61, s0
	v_readlane_b32 s0, v252, 0
	v_readlane_b32 s1, v252, 1
	s_add_u32 s52, s0, s52
	v_add_u32_e32 v69, v68, v60
	v_ashrrev_i32_e32 v89, 31, v88
	v_add3_u32 v113, 0, v61, v60
	s_addc_u32 s53, s1, 0
	v_add3_u32 v60, s93, v67, v66
	v_readlane_b32 s0, v255, 26
	v_lshlrev_b32_e32 v70, 4, v98
	v_add_u32_e32 v109, v68, v61
	v_lshl_add_u64 v[90:91], v[88:89], 1, s[52:53]
	v_lshl_add_u32 v89, v60, 2, s0
	v_readlane_b32 s0, v255, 27
	v_mov_b32_e32 v165, v164
	v_lshlrev_b32_e32 v97, 2, v98
	v_add_u32_e32 v99, 0, v70
	v_lshl_add_u32 v100, v88, 2, 0
	v_add_u32_e32 v105, 0xfffffe80, v104
	v_add_u32_e32 v106, 0xffffff00, v104
	v_add_u32_e32 v107, 0xffffff80, v104
	v_add_u32_e32 v110, 0xfffffe80, v109
	v_add_u32_e32 v111, 0xffffff00, v109
	v_add_u32_e32 v112, 0xffffff80, v109
	v_add_u32_e32 v114, s0, v70
	v_add_u32_e32 v115, v69, v64
	v_add_u32_e32 v116, v62, v63
	v_mov_b64_e32 v[60:61], v[164:165]
	v_mov_b64_e32 v[62:63], v[164:165]
	s_waitcnt lgkmcnt(0)
	s_barrier
	v_readlane_b32 s2, v252, 2
	v_readlane_b32 s3, v252, 3
	v_readlane_b32 s4, v252, 4
	v_readlane_b32 s5, v252, 5
	v_readlane_b32 s6, v252, 6
	v_readlane_b32 s7, v252, 7
	v_readlane_b32 s8, v252, 8
	v_readlane_b32 s9, v252, 9
	v_readlane_b32 s10, v252, 10
	v_readlane_b32 s11, v252, 11
	v_readlane_b32 s12, v252, 12
	v_readlane_b32 s13, v252, 13
	v_readlane_b32 s14, v252, 14
	v_readlane_b32 s15, v252, 15

; __device__ __forceinline__ int launder(int x) { asm volatile("" : "+v"(x)); return x; }
; template <bool DUAL>
; __device__ __forceinline__ void rwkv_tile(const Params& p, int l, int tile, unsigned char* smem) {
;     ...
;   const int tid = launder(threadIdx.x), lane = tid & 63, w = tid >> 6, fr = lane & 15, fq = lane >> 4;
;   const int row = rg * 16 + w * 4 + fq;
;   const int c0 = fr * 4;
;   const int ld2 = l * 2 + d;
;   const size_t rowbase = (size_t)b * TPB;
;   const int lc = (tid & 15) * 4;
;   const float* mu0 = p.rwkv_mu + (size_t)(l * 2 + 0) * 1024 + h * 64 + lc;
;   const float* mu1 = p.rwkv_mu + (size_t)(l * 2 + 1) * 1024 + h * 64 + lc;
;   const float4 m0r = *(const float4*)mu0, m1r = *(const float4*)mu1;
;   const float4 m0k = *(const float4*)(mu0 + 256), m1k = *(const float4*)(mu1 + 256);
;   const float4 m0v = *(const float4*)(mu0 + 512), m1v = *(const float4*)(mu1 + 512);
;   const float4 ka4 = *(const float4*)(p.rwkv_k_a + ld2 * 256 + h * 64 + lc);
;   v2f sA = {0.f, 0.f}, sB = {0.f, 0.f};
;   v2f iA = {(row == c0) ? 1.f : 0.f, (row == c0 + 1) ? 1.f : 0.f}, iB = {(row == c0 + 2) ? 1.f : 0.f, (row == c0 + 3) ? 1.f : 0.f};
;   const int pcc = tid % 24, prow = tid / 24;
;   const bool pact = tid < 240;
;   const bf16_t* rbase_g = p.PR + rowbase * 1024 + (pcc >> 3) * 256 + h * 64 + (pcc & 7) * 8;
;   const bf16_t* pbase_g = p.PRE + (size_t)(pcc >> 3) * PRE_ARR + (rowbase * 2 + d) * 256 + h * 64 + (pcc & 7) * 8;
;   uint4 pf0, pf1, pf2, pf3, pg0, pg1, pg2, pg3;
.LBB0_1409:
	s_or_b64 exec, exec, s[48:49]
	v_and_b32_e32 v101, 15, v61
	v_bfe_u32 v68, v61, 4, 2
	v_ashrrev_i32_e32 v61, 4, v61
	v_and_b32_e32 v66, -4, v61
	v_readlane_b32 s0, v253, 62
	v_lshlrev_b32_e32 v67, 2, v101
	v_lshl_add_u32 v62, v62, 1, 0
	v_add_u32_e32 v69, s0, v66
	v_or_b32_e32 v66, v69, v68
	v_cmp_eq_u32_e32 vcc, v66, v67
	v_or_b32_e32 v70, 1, v67
	v_lshl_add_u32 v105, v64, 1, v62
	v_lshl_add_u32 v106, v65, 1, v62
	v_add_u32_e32 v64, 1, v61
	v_sub_u32_e32 v65, 32, v61
	v_cndmask_b32_e64 v88, 0, 1.0, vcc
	v_cmp_eq_u32_e32 vcc, v66, v70
	v_or_b32_e32 v70, 2, v67
	v_lshlrev_b32_e32 v60, 1, v60
	s_movk_i32 s0, 0x180
	v_cndmask_b32_e64 v64, v65, v64, s[36:37]
	v_cndmask_b32_e64 v89, 0, 1.0, vcc
	v_cmp_eq_u32_e32 vcc, v66, v70
	v_add_u32_e32 v70, 0, v60
	v_mul_lo_u32 v64, v64, s0
	s_movk_i32 s1, 0x600
	v_add_u32_e32 v107, v70, v64
	v_add3_u32 v111, 0, v64, v60
	v_mul_lo_u32 v64, v61, s1
	v_add_u32_e32 v65, 17, v61
	v_sub_u32_e32 v61, 16, v61
	v_or_b32_e32 v67, 3, v67
	v_cndmask_b32_e64 v61, v61, v65, s[36:37]
	v_cndmask_b32_e64 v90, 0, 1.0, vcc
	v_cmp_eq_u32_e32 vcc, v66, v67
	v_ashrrev_i32_e32 v67, 31, v66
	v_lshl_add_u32 v104, v63, 1, v62
	v_mul_lo_u32 v63, v100, s0
	v_mul_lo_u32 v61, v61, s0
	v_readlane_b32 s0, v254, 21
	v_add_u32_e32 v71, v70, v60
	v_add_u32_e32 v112, v70, v61
	v_add3_u32 v116, 0, v61, v60
	v_lshlrev_b64 v[60:61], 1, v[66:67]
	v_readlane_b32 s1, v254, 22
	v_lshlrev_b32_e32 v72, 4, v101
	v_mov_b32_e32 v165, v164
	v_lshl_add_u64 v[84:85], s[0:1], 0, v[60:61]
	v_readlane_b32 s0, v254, 23
	v_readlane_b32 s1, v254, 24
	v_cndmask_b32_e64 v91, 0, 1.0, vcc
	v_add_u32_e32 v102, 0, v72
	v_lshl_add_u64 v[86:87], s[0:1], 0, v[60:61]
	v_add_u32_e32 v60, v69, v68
	v_readlane_b32 s0, v255, 26
	v_lshl_add_u32 v103, v66, 2, 0
	v_add_u32_e32 v108, 0xfffffe80, v107
	v_lshl_add_u32 v117, v60, 2, s0
	v_readlane_b32 s0, v255, 27
	v_add_u32_e32 v109, 0xffffff00, v107
	v_add_u32_e32 v110, 0xffffff80, v107
	v_add_u32_e32 v113, 0xfffffe80, v112
	v_add_u32_e32 v114, 0xffffff00, v112
	v_add_u32_e32 v115, 0xffffff80, v112
	v_add_u32_e32 v118, s0, v72
	s_movk_i32 s28, 0x58
	v_add_u32_e32 v119, v71, v64
	v_add_u32_e32 v120, v62, v63
	v_mov_b64_e32 v[94:95], v[164:165]
	v_mov_b64_e32 v[92:93], v[164:165]
	s_waitcnt lgkmcnt(0)
	s_barrier
	s_branch .LBB0_1411

; __device__ __forceinline__ bf16_t f2bf(float f) { return (bf16_t)(pack2(f, 0.f) & 0xffffu); }
; template <bool DUAL>
; __device__ __forceinline__ void rwkv_tile(const Params& p, int l, int tile, unsigned char* smem) {
;     ...
;     int plo, slo, shi;
;     RW_GEOM(cix, plo, slo, shi);
;     ...
;           const int ri = (d == 0) ? ii + 1 : 32 - ii;
;           const int pi = plo - 1 + ri;
;           p.yR[((size_t)d * TOK + rowbase + pi) * 256 + h * 64 + row] = f2bf(ykeep);
;           if (DUAL) p.GID[((size_t)(d * 4 + b) * NSEG1 + (cix - CSPLIT) * 32 + ii) * 256 + h * 64 + row] = f2bf(gkeep);
.LBB0_1429:
	s_lshl_b32 s53, s28, 5
	s_sub_i32 s28, 0x11e0, s53
	s_and_b64 s[50:51], s[36:37], exec
	s_cselect_b32 s28, s53, s28
	s_addk_i32 s53, 0xf500
	s_add_i32 s28, s28, -1
	s_ashr_i32 s50, s53, 31
	v_readlane_b32 s0, v254, 37
	s_add_u32 s53, s53, s0
	s_addc_u32 s54, s50, 0
	s_branch .Lrw_du_scan
